# stick-breaking wave items: static per-wave item order replaces the single-counter work queue (counter atomics were saturating)
# speedup vs baseline: 1.0638x; 1.0638x over previous
; #define GPTR(p) gptr_(p)
; #define OPQ(x) asm volatile("" : "+s"(x))
; #define OPQP(T, x) do { unsigned long long xi_ = (unsigned long long)(x); asm volatile("" : "+s"(xi_)); x = (T*)(__attribute__((address_space(1))) T*)xi_; } while (0)
; __global__ void __launch_bounds__(512, 2) mega_fwd(Args args) {
;     ...
;                 if (ph == 0) { unsigned char* w2 = ws; float* o2 = out; int l2 = l; OPQP(unsigned char, w2); OPQP(float, o2); OPQ(l2);
;                     const unsigned long long* tab2 = (const unsigned long long*)w2; unsigned* ctr2 = (unsigned*)(w2 + WS_CTR) + 2 * l2 + 1;
;                     unsigned wq = 0; if (lane == 0) wq = atomicAdd(ctr2, 1u); int w = __builtin_amdgcn_readfirstlane(wq);
;                     while (w < 4352) { unsigned wn = 0; if (lane == 0) wn = atomicAdd(ctr2, 1u);
;                         int lane2 = lane; asm volatile("" : "+v"(lane2));
;                         if (w < 256) sb_item<true>(4096 + w, l2, (const float*)(w2 + WS_PROJ), o2 + O_KP + (size_t)l2 * NPROMPT * 512, o2 + O_VP + (size_t)l2 * NPROMPT * 512,
;                                                     o2 + O_KS + (size_t)l2 * 262144, o2 + O_VS + (size_t)l2 * 262144, GPTR(tab2[3]), GPTR(tab2[4]), (const bf16_t*)(w2 + WS_VT), (const bf16_t*)(w2 + WS_KB), (float*)(w2 + WS_OSB), lane2);
;                         else sb_item<false>(w - 256, l2, (const float*)(w2 + WS_PROJ), o2 + O_KP + (size_t)l2 * NPROMPT * 512, o2 + O_VP + (size_t)l2 * NPROMPT * 512,
;                                                     o2 + O_KS + (size_t)l2 * 262144, o2 + O_VS + (size_t)l2 * 262144, GPTR(tab2[3]), GPTR(tab2[4]), (const bf16_t*)(w2 + WS_VT), (const bf16_t*)(w2 + WS_KB), (float*)(w2 + WS_OSB), lane2);
;                         w = __builtin_amdgcn_readfirstlane(wn); } }
.LBB0_1666:
	s_andn2_b64 vcc, exec, s[80:81]
	v_readlane_b32 s81, v254, 37
	s_cbranch_vccnz .LBB0_1696
	v_readlane_b32 s0, v253, 38
	v_readlane_b32 s1, v253, 39
	v_readlane_b32 s2, v253, 40
	v_readlane_b32 s3, v253, 41
	s_mov_b64 s[4:5], s[0:1]
	v_readlane_b32 s0, v254, 42
	s_mov_b64 s[8:9], s[2:3]
	s_mov_b32 s2, s0
	s_lshl_b32 s0, s2, 1
	s_ashr_i32 s1, s0, 31
	s_lshl_b64 s[0:1], s[0:1], 2
	s_add_u32 s0, s8, s0
	s_addc_u32 s1, s9, s1
	s_add_u32 s10, s0, 0x14004
	s_addc_u32 s11, s1, 0
	s_waitcnt vmcnt(0)
	v_lshrrev_b32_e32 v0, 6, v222
	s_lshl_b32 s3, s81, 3
	s_movk_i32 s99, 0xff00
	v_readfirstlane_b32 s27, v0
	s_add_i32 s27, s27, s3
	s_cmpk_lt_u32 s27, 0x100
	s_cselect_b32 s98, 0x1000, s99
	s_add_i32 s27, s27, s98
.LBB0_1671:
	s_cmpk_gt_i32 s27, 0x10ff
	s_cbranch_scc1 .LBB0_1696
	s_add_u32 s12, s8, 0x10000000
	s_addc_u32 s13, s9, 0
	s_add_u32 s20, s8, 0x3ac00000
	s_addc_u32 s21, s9, 0
	s_add_u32 s14, s8, 0x3c000000
	s_addc_u32 s15, s9, 0
	s_add_u32 s16, s8, 0x20000000
	s_addc_u32 s17, s9, 0
	s_ashr_i32 s3, s2, 31
	s_lshl_b64 s[6:7], s[2:3], 20
	s_add_u32 s3, s4, s6
	s_addc_u32 s4, s5, s7
	s_add_u32 s22, s3, 0xc700000
	s_addc_u32 s23, s4, 0
	s_add_u32 s24, s3, 0xc900000
	s_addc_u32 s25, s4, 0
	s_lshl_b32 s26, s2, 16
	s_branch .LBB0_1674

; #define GPTR(p) gptr_(p)
; template <bool SAMPLE> __device__ __forceinline__ void sb_item(int item, int layer, const float* PROJ, const float* KP, const float* VP, const float* KS, const float* VS, ...
;     ...
;     if (!SAMPLE) { const int b = item >> 11, rem = item & 2047, qt = rem & 255; h = rem >> 8; VTh = VT + ((size_t)(b * 8 + h) * 2048 * 64 + r32) * 4; KBh = KB + ((size_t)(b * 8 + h) * 256 * 8 * 32 + hi * 32 + r32) * 8;
;         qrow = b * 8192 + qt * 32 + r32; qpos = qt * 32 + r32; qvalid = true; ptop = qt * 32; split = 1 << 30; qmin = qt * 32;
;         kA = KP + (size_t)(b * 8192) * 512 + h * 64; vA = VP + (size_t)(b * 8192) * 512 + h * 64; kB = kA; vB = vA;
;     } else { const int it = item - 4096, s = it >> 3; h = it & 7;
;         qrow = NPROMPT + s * 16 + (r32 & 15); qpos = 2048 + (r32 & 15); qvalid = r32 < 16; ptop = 2032; split = 2048; qmin = 2048;
;         kA = CK + (size_t)((layer * 32 + s) * 2048) * 512 + h * 64; vA = CV + (size_t)((layer * 32 + s) * 2048) * 512 + h * 64;
;         kB = KS + ((long)(s * 16) - 2048) * 512 + h * 64; vB = VS + ((long)(s * 16) - 2048) * 512 + h * 64; }
;     bf16x8 qh[4];
;     { const bf16_t* qp = (const bf16_t*)PROJ + (size_t)qrow * PLD + h * 64 + 8 * hi;
; #pragma unroll
; __global__ void __launch_bounds__(512, 2) mega_fwd(Args args) {
;     ...
;                     while (w < 4352) { unsigned wn = 0; if (lane == 0) wn = atomicAdd(ctr2, 1u);
;                         int lane2 = lane; asm volatile("" : "+v"(lane2));
;                         if (w < 256) sb_item<true>(4096 + w, l2, (const float*)(w2 + WS_PROJ), o2 + O_KP + (size_t)l2 * NPROMPT * 512, o2 + O_VP + (size_t)l2 * NPROMPT * 512,
;                                                     o2 + O_KS + (size_t)l2 * 262144, o2 + O_VS + (size_t)l2 * 262144, GPTR(tab2[3]), GPTR(tab2[4]), (const bf16_t*)(w2 + WS_VT), (const bf16_t*)(w2 + WS_KB), (float*)(w2 + WS_OSB), lane2);
;                         else sb_item<false>(w - 256, l2, (const float*)(w2 + WS_PROJ), o2 + O_KP + (size_t)l2 * NPROMPT * 512, o2 + O_VP + (size_t)l2 * NPROMPT * 512,
;                                                     o2 + O_KS + (size_t)l2 * 262144, o2 + O_VS + (size_t)l2 * 262144, GPTR(tab2[3]), GPTR(tab2[4]), (const bf16_t*)(w2 + WS_VT), (const bf16_t*)(w2 + WS_KB), (float*)(w2 + WS_OSB), lane2);
;                         w = __builtin_amdgcn_readfirstlane(wn); } }
.LBB0_1674:
	s_mov_b32 s99, 0xfffff700
	s_cmpk_lt_u32 s27, 0x1000
	s_cselect_b32 s98, 0x800, s99
	s_add_i32 s98, s27, s98
	s_cmpk_ge_u32 s98, 0x1000
	s_cselect_b32 s98, 0x7fff, s98
	v_mov_b32_e32 v160, s98
.LBB0_1678:
	v_mov_b32_e32 v99, v159
	s_cmpk_gt_i32 s27, 0xff
	v_ashrrev_i32_e32 v105, 5, v99
	v_and_b32_e32 v108, 31, v99
	v_cmp_gt_u32_e64 s[4:5], 32, v99
	v_lshlrev_b32_e32 v96, 3, v105
	v_lshlrev_b32_e32 v161, 2, v105
	s_cbranch_scc0 .LBB0_1685
	s_add_i32 s18, s27, 0xffffff00
	s_lshr_b32 s19, s18, 11
	s_bfe_u32 s29, s18, 0x30008
	s_lshl_b32 s2, s19, 3
	s_or_b32 s86, s2, s29
	v_and_b32_e32 v0, 0xffffffe0, v99
	s_lshl_b64 s[6:7], s[86:87], 16
	v_ashrrev_i32_e32 v1, 31, v0
	v_lshl_add_u64 v[0:1], s[6:7], 0, v[0:1]
	s_lshl_b32 s7, s18, 5
	s_lshl_b32 s6, s19, 13
	s_and_b32 s28, s7, 0x1fe0
	s_lshl_b64 s[2:3], s[86:87], 20
	s_or_b32 s6, s6, s28
	s_lshl_b32 s86, s29, 6
	v_or_b32_e32 v110, s6, v108
	s_mov_b64 s[18:19], s[86:87]
	v_mov_b64_e32 v[2:3], s[12:13]
	s_lshl_b32 s86, s29, 7
	v_or_b32_e32 v0, v0, v108
	v_mad_u64_u32 v[2:3], s[6:7], v110, s93, v[2:3]
	s_add_u32 s2, s20, s2
	v_lshlrev_b32_e32 v192, 3, v108
	v_lshl_add_u64 v[2:3], v[2:3], 0, s[86:87]
	v_ashrrev_i32_e32 v97, 31, v96
	s_addc_u32 s3, s21, s3
	v_lshl_add_u64 v[100:101], v[0:1], 4, s[14:15]
	s_lshl_b32 s86, s28, 7
	v_lshl_add_u64 v[2:3], v[96:97], 1, v[2:3]
	v_lshl_add_u64 v[102:103], s[2:3], 0, v[192:193]
	v_lshl_add_u64 v[0:1], v[100:101], 0, s[86:87]
	s_lshr_b32 s2, s28, 2
	global_load_dwordx4 v[48:51], v[2:3], off
	global_load_dwordx4 v[52:55], v[2:3], off offset:32
	global_load_dwordx4 v[56:59], v[2:3], off offset:64
	global_load_dwordx4 v[60:63], v[2:3], off offset:96
	global_load_dwordx4 v[64:67], v[0:1], off
	global_load_dwordx4 v[68:71], v[0:1], off offset:1024
	global_load_dwordx4 v[72:75], v[0:1], off offset:2048
	global_load_dwordx4 v[76:79], v[0:1], off offset:3072
	v_add_u32_e32 v0, s2, v105
	v_ashrrev_i32_e32 v1, 31, v0
	v_lshlrev_b64 v[0:1], 9, v[0:1]
	v_lshl_add_u64 v[0:1], v[102:103], 0, v[0:1]
	global_load_dwordx2 v[92:93], v[0:1], off
	global_load_dwordx2 v[94:95], v[0:1], off offset:1024
	global_load_dwordx2 v[90:91], v[0:1], off offset:1280
	global_load_dwordx2 v[88:89], v[0:1], off offset:256
	global_load_dwordx2 v[84:85], v[0:1], off offset:2048
	global_load_dwordx2 v[86:87], v[0:1], off offset:3072
	global_load_dwordx2 v[82:83], v[0:1], off offset:3328
	global_load_dwordx2 v[80:81], v[0:1], off offset:2304
	v_or_b32_e32 v104, s28, v108
	v_mov_b32_e32 v109, 0
	v_mov_b32_e32 v111, v193
	v_lshlrev_b32_e32 v98, 2, v105
	v_mov_b32_e32 v97, v104
	s_mov_b32 s29, s28
	v_mov_b32_e32 v0, 0
	v_mov_b32_e32 v1, v109
	v_mov_b32_e32 v2, v109
	v_mov_b32_e32 v3, v109
	v_mov_b32_e32 v4, v109
	v_mov_b32_e32 v5, v109
	v_mov_b32_e32 v6, v109
	v_mov_b32_e32 v7, v109
	v_mov_b32_e32 v8, v109
	v_mov_b32_e32 v9, v109
	v_mov_b32_e32 v10, v109
	v_mov_b32_e32 v11, v109
	v_mov_b32_e32 v12, v109
	v_mov_b32_e32 v13, v109
	v_mov_b32_e32 v14, v109
	v_mov_b32_e32 v15, v109
	v_mov_b32_e32 v16, 0
	v_mov_b32_e32 v17, v109
	v_mov_b32_e32 v18, v109
	v_mov_b32_e32 v19, v109
	v_mov_b32_e32 v20, v109
	v_mov_b32_e32 v21, v109
	v_mov_b32_e32 v22, v109
	v_mov_b32_e32 v23, v109
	v_mov_b32_e32 v24, v109
	v_mov_b32_e32 v25, v109
	v_mov_b32_e32 v26, v109
	v_mov_b32_e32 v27, v109
	v_mov_b32_e32 v28, v109
	v_mov_b32_e32 v29, v109
	v_mov_b32_e32 v30, v109
	v_mov_b32_e32 v31, v109
	s_branch .LBB0_1681
